# ssm_tables (per-layer SSM table build in the W_in phase slack): copy loop and Toeplitz-row loop unrolled so their loads are in flight together
# speedup vs baseline: 1.0055x; 1.0055x over previous
; __device__ __forceinline__ u32x4 pack8(const f32x4 a, const f32x4 b) { u32x4 w; w.x = cvt_pk_bf16(a[0], a[1]); w.y = cvt_pk_bf16(a[2], a[3]); w.z = cvt_pk_bf16(b[0], b[1]); w.w = cvt_pk_bf16(b[2], b[3]); return w; }
; __device__ __forceinline__ void ssm_tables(unsigned char* smem, const Params& P, int layer, int job0, int job1, int jstep) {
;     ...
;     for (int job = job0; job < job1; job += jstep) { const int g = job >> 3, sub = job & 7;
;         __syncthreads(); { const float2* src = (const float2*)(P.ws + OFF_GT) + (size_t)(layer * 32 + g) * 4160; for (int i = tid; i < 4160; i += 512) AT[i] = src[i]; } __syncthreads();
;         bf16_t* Tg = (bf16_t*)(P.ws + OFF_TG) + (size_t)g * 768 * 512; bf16_t* Mo = (bf16_t*)(P.ws + OFF_MO) + (size_t)g * 512 * 256; const float* Kg = Kt + (size_t)g * 8192;
;         for (int i = tid; i < 64 * 64; i += 512) { const int rl = i >> 6, pc = i & 63, t = 4 * sub + (rl >> 4), p = rl & 15, s = pc >> 1, q0 = (pc & 1) * 8; u32x4 w = {0u, 0u, 0u, 0u};
;             if (t >= s) { const float* kp = Kg + (size_t)(t - s) * 256 + p * 16 + q0; w = pack8(*(const f32x4*)kp, *(const f32x4*)(kp + 4)); }
;             *(u32x4*)(Tg + (size_t)(t * 16 + p) * 512 + pc * 8) = w; }
.LBB0_372:
	s_ashr_i32 s20, s37, 3
	s_waitcnt vmcnt(0)
	s_barrier
	s_and_saveexec_b64 s[22:23], s[6:7]
	s_movk_i32 s5, 0xe3f
	s_cbranch_execz .LBB0_375
	v_readlane_b32 s4, v231, 61
	s_add_i32 s4, s4, s20
	v_mad_i64_i32 v[8:9], s[24:25], s4, v194, v[16:17]
	global_load_dwordx2 v[60:61], v[8:9], off
	v_lshl_add_u64 v[8:9], v[8:9], 0, s[80:81]
	global_load_dwordx2 v[62:63], v[8:9], off
	v_lshl_add_u64 v[8:9], v[8:9], 0, s[80:81]
	global_load_dwordx2 v[64:65], v[8:9], off
	v_lshl_add_u64 v[8:9], v[8:9], 0, s[80:81]
	global_load_dwordx2 v[66:67], v[8:9], off
	v_lshl_add_u64 v[8:9], v[8:9], 0, s[80:81]
	global_load_dwordx2 v[68:69], v[8:9], off
	v_lshl_add_u64 v[8:9], v[8:9], 0, s[80:81]
	global_load_dwordx2 v[70:71], v[8:9], off
	v_lshl_add_u64 v[8:9], v[8:9], 0, s[80:81]
	global_load_dwordx2 v[72:73], v[8:9], off
	v_lshl_add_u64 v[8:9], v[8:9], 0, s[80:81]
	global_load_dwordx2 v[74:75], v[8:9], off
	v_lshl_add_u64 v[8:9], v[8:9], 0, s[80:81]
	v_cmp_gt_u32_e32 vcc, 64, v2
	s_and_saveexec_b64 s[24:25], vcc
	s_cbranch_execz .Ltab_c8
	global_load_dwordx2 v[76:77], v[8:9], off
.Ltab_c8:
	s_or_b64 exec, exec, s[24:25]
	s_waitcnt vmcnt(0)
	ds_write_b64 v22, v[60:61]
	ds_write_b64 v22, v[62:63] offset:4096
	ds_write_b64 v22, v[64:65] offset:8192
	ds_write_b64 v22, v[66:67] offset:12288
	ds_write_b64 v22, v[68:69] offset:16384
	ds_write_b64 v22, v[70:71] offset:20480
	ds_write_b64 v22, v[72:73] offset:24576
	ds_write_b64 v22, v[74:75] offset:28672
	s_and_saveexec_b64 s[24:25], vcc
	ds_write_b64 v22, v[76:77] offset:32768
	s_or_b64 exec, exec, s[24:25]
.LBB0_375:
	s_or_b64 exec, exec, s[22:23]
	s_and_b32 s38, s37, 7
	s_ashr_i32 s21, s20, 31
	s_mul_i32 s5, s20, 0xc0000
	s_mul_hi_i32 s4, s20, 0xc0000
	s_add_u32 s24, s35, s5
	s_addc_u32 s25, s36, s4
	v_lshlrev_b32_e32 v18, 1, v12
	s_waitcnt lgkmcnt(0)
	s_barrier
	s_and_saveexec_b64 s[22:23], s[8:9]
	s_cbranch_execz .LBB0_380
	s_lshl_b64 s[26:27], s[20:21], 15
	s_add_u32 s26, s33, s26
	v_mov_b32_e32 v19, v1
	s_addc_u32 s27, s34, s27
	s_lshl_b32 s39, s38, 2
	v_lshl_add_u64 v[20:21], s[24:25], 0, v[18:19]
	v_and_b32_e32 v10, 8, v13
	v_lshlrev_b32_e32 v10, 2, v10
	v_mov_b32_e32 v19, v2
	v_ashrrev_i32_e32 v0, 10, v19
	v_add_u32_e32 v26, s39, v0
	v_bfe_u32 v27, v19, 6, 4
	v_lshl_or_b32 v28, v26, 4, v27
	v_ashrrev_i32_e32 v29, 31, v28
	v_lshlrev_b64 v[28:29], 10, v[28:29]
	v_lshl_add_u64 v[144:145], v[20:21], 0, v[28:29]
	v_mov_b32_e32 v80, 0
	v_mov_b32_e32 v81, 0
	v_mov_b32_e32 v82, 0
	v_mov_b32_e32 v83, 0
	v_mov_b32_e32 v84, 0
	v_mov_b32_e32 v85, 0
	v_mov_b32_e32 v86, 0
	v_mov_b32_e32 v87, 0
	v_cmp_ge_i32_e32 vcc, v26, v23
	s_and_saveexec_b64 s[30:31], vcc
	s_cbranch_execz .Ltab_t0
	v_sub_u32_e32 v0, v26, v23
	v_lshlrev_b64 v[8:9], 10, v[0:1]
	v_lshl_add_u64 v[8:9], s[26:27], 0, v[8:9]
	v_lshlrev_b32_e32 v0, 6, v27
	v_lshl_add_u64 v[8:9], v[8:9], 0, v[0:1]
	v_mov_b32_e32 v0, v10
	v_lshl_add_u64 v[8:9], v[8:9], 0, v[0:1]
	global_load_dwordx4 v[80:83], v[8:9], off
	global_load_dwordx4 v[84:87], v[8:9], off offset:16
.Ltab_t0:
	s_or_b64 exec, exec, s[30:31]
	v_add_u32_e32 v19, 0x200, v2
	v_ashrrev_i32_e32 v0, 10, v19
	v_add_u32_e32 v26, s39, v0
	v_bfe_u32 v27, v19, 6, 4
	v_lshl_or_b32 v28, v26, 4, v27
	v_ashrrev_i32_e32 v29, 31, v28
	v_lshlrev_b64 v[28:29], 10, v[28:29]
	v_lshl_add_u64 v[146:147], v[20:21], 0, v[28:29]
	v_mov_b32_e32 v88, 0
	v_mov_b32_e32 v89, 0
	v_mov_b32_e32 v90, 0
	v_mov_b32_e32 v91, 0
	v_mov_b32_e32 v92, 0
	v_mov_b32_e32 v93, 0
	v_mov_b32_e32 v94, 0
	v_mov_b32_e32 v95, 0
	v_cmp_ge_i32_e32 vcc, v26, v23
	s_and_saveexec_b64 s[30:31], vcc
	s_cbranch_execz .Ltab_t1
	v_sub_u32_e32 v0, v26, v23
	v_lshlrev_b64 v[8:9], 10, v[0:1]
	v_lshl_add_u64 v[8:9], s[26:27], 0, v[8:9]
	v_lshlrev_b32_e32 v0, 6, v27
	v_lshl_add_u64 v[8:9], v[8:9], 0, v[0:1]
	v_mov_b32_e32 v0, v10
	v_lshl_add_u64 v[8:9], v[8:9], 0, v[0:1]
	global_load_dwordx4 v[88:91], v[8:9], off
	global_load_dwordx4 v[92:95], v[8:9], off offset:16
.Ltab_t1:
	s_or_b64 exec, exec, s[30:31]
	v_add_u32_e32 v19, 0x400, v2
	v_ashrrev_i32_e32 v0, 10, v19
	v_add_u32_e32 v26, s39, v0
	v_bfe_u32 v27, v19, 6, 4
	v_lshl_or_b32 v28, v26, 4, v27
	v_ashrrev_i32_e32 v29, 31, v28
	v_lshlrev_b64 v[28:29], 10, v[28:29]
	v_lshl_add_u64 v[148:149], v[20:21], 0, v[28:29]
	v_mov_b32_e32 v96, 0
	v_mov_b32_e32 v97, 0
	v_mov_b32_e32 v98, 0
	v_mov_b32_e32 v99, 0
	v_mov_b32_e32 v100, 0
	v_mov_b32_e32 v101, 0
	v_mov_b32_e32 v102, 0
	v_mov_b32_e32 v103, 0
	v_cmp_ge_i32_e32 vcc, v26, v23
	s_and_saveexec_b64 s[30:31], vcc
	s_cbranch_execz .Ltab_t2
	v_sub_u32_e32 v0, v26, v23
	v_lshlrev_b64 v[8:9], 10, v[0:1]
	v_lshl_add_u64 v[8:9], s[26:27], 0, v[8:9]
	v_lshlrev_b32_e32 v0, 6, v27
	v_lshl_add_u64 v[8:9], v[8:9], 0, v[0:1]
	v_mov_b32_e32 v0, v10
	v_lshl_add_u64 v[8:9], v[8:9], 0, v[0:1]
	global_load_dwordx4 v[96:99], v[8:9], off
	global_load_dwordx4 v[100:103], v[8:9], off offset:16
.Ltab_t2:
	s_or_b64 exec, exec, s[30:31]
	v_add_u32_e32 v19, 0x600, v2
	v_ashrrev_i32_e32 v0, 10, v19
	v_add_u32_e32 v26, s39, v0
	v_bfe_u32 v27, v19, 6, 4
	v_lshl_or_b32 v28, v26, 4, v27
	v_ashrrev_i32_e32 v29, 31, v28
	v_lshlrev_b64 v[28:29], 10, v[28:29]
	v_lshl_add_u64 v[150:151], v[20:21], 0, v[28:29]
	v_mov_b32_e32 v104, 0
	v_mov_b32_e32 v105, 0
	v_mov_b32_e32 v106, 0
	v_mov_b32_e32 v107, 0
	v_mov_b32_e32 v108, 0
	v_mov_b32_e32 v109, 0
	v_mov_b32_e32 v110, 0
	v_mov_b32_e32 v111, 0
	v_cmp_ge_i32_e32 vcc, v26, v23
	s_and_saveexec_b64 s[30:31], vcc
	s_cbranch_execz .Ltab_t3
	v_sub_u32_e32 v0, v26, v23
	v_lshlrev_b64 v[8:9], 10, v[0:1]
	v_lshl_add_u64 v[8:9], s[26:27], 0, v[8:9]
	v_lshlrev_b32_e32 v0, 6, v27
	v_lshl_add_u64 v[8:9], v[8:9], 0, v[0:1]
	v_mov_b32_e32 v0, v10
	v_lshl_add_u64 v[8:9], v[8:9], 0, v[0:1]
	global_load_dwordx4 v[104:107], v[8:9], off
	global_load_dwordx4 v[108:111], v[8:9], off offset:16
; __device__ __forceinline__ u32x4 pack8(const f32x4 a, const f32x4 b) { u32x4 w; w.x = cvt_pk_bf16(a[0], a[1]); w.y = cvt_pk_bf16(a[2], a[3]); w.z = cvt_pk_bf16(b[0], b[1]); w.w = cvt_pk_bf16(b[2], b[3]); return w; }
; __device__ __forceinline__ void ssm_tables(unsigned char* smem, const Params& P, int layer, int job0, int job1, int jstep) {
;     ...
;         for (int i = tid; i < 64 * 64; i += 512) { const int rl = i >> 6, pc = i & 63, t = 4 * sub + (rl >> 4), p = rl & 15, s = pc >> 1, q0 = (pc & 1) * 8; u32x4 w = {0u, 0u, 0u, 0u};
;             if (t >= s) { const float* kp = Kg + (size_t)(t - s) * 256 + p * 16 + q0; w = pack8(*(const f32x4*)kp, *(const f32x4*)(kp + 4)); }
;             *(u32x4*)(Tg + (size_t)(t * 16 + p) * 512 + pc * 8) = w; }
.Ltab_t3:
	s_or_b64 exec, exec, s[30:31]
	v_add_u32_e32 v19, 0x800, v2
	v_ashrrev_i32_e32 v0, 10, v19
	v_add_u32_e32 v26, s39, v0
	v_bfe_u32 v27, v19, 6, 4
	v_lshl_or_b32 v28, v26, 4, v27
	v_ashrrev_i32_e32 v29, 31, v28
	v_lshlrev_b64 v[28:29], 10, v[28:29]
	v_lshl_add_u64 v[152:153], v[20:21], 0, v[28:29]
	v_mov_b32_e32 v112, 0
	v_mov_b32_e32 v113, 0
	v_mov_b32_e32 v114, 0
	v_mov_b32_e32 v115, 0
	v_mov_b32_e32 v116, 0
	v_mov_b32_e32 v117, 0
	v_mov_b32_e32 v118, 0
	v_mov_b32_e32 v119, 0
	v_cmp_ge_i32_e32 vcc, v26, v23
	s_and_saveexec_b64 s[30:31], vcc
	s_cbranch_execz .Ltab_t4
	v_sub_u32_e32 v0, v26, v23
	v_lshlrev_b64 v[8:9], 10, v[0:1]
	v_lshl_add_u64 v[8:9], s[26:27], 0, v[8:9]
	v_lshlrev_b32_e32 v0, 6, v27
	v_lshl_add_u64 v[8:9], v[8:9], 0, v[0:1]
	v_mov_b32_e32 v0, v10
	v_lshl_add_u64 v[8:9], v[8:9], 0, v[0:1]
	global_load_dwordx4 v[112:115], v[8:9], off
	global_load_dwordx4 v[116:119], v[8:9], off offset:16
.Ltab_t4:
	s_or_b64 exec, exec, s[30:31]
	v_add_u32_e32 v19, 0xa00, v2
	v_ashrrev_i32_e32 v0, 10, v19
	v_add_u32_e32 v26, s39, v0
	v_bfe_u32 v27, v19, 6, 4
	v_lshl_or_b32 v28, v26, 4, v27
	v_ashrrev_i32_e32 v29, 31, v28
	v_lshlrev_b64 v[28:29], 10, v[28:29]
	v_lshl_add_u64 v[154:155], v[20:21], 0, v[28:29]
	v_mov_b32_e32 v120, 0
	v_mov_b32_e32 v121, 0
	v_mov_b32_e32 v122, 0
	v_mov_b32_e32 v123, 0
	v_mov_b32_e32 v124, 0
	v_mov_b32_e32 v125, 0
	v_mov_b32_e32 v126, 0
	v_mov_b32_e32 v127, 0
	v_cmp_ge_i32_e32 vcc, v26, v23
	s_and_saveexec_b64 s[30:31], vcc
	s_cbranch_execz .Ltab_t5
	v_sub_u32_e32 v0, v26, v23
	v_lshlrev_b64 v[8:9], 10, v[0:1]
	v_lshl_add_u64 v[8:9], s[26:27], 0, v[8:9]
	v_lshlrev_b32_e32 v0, 6, v27
	v_lshl_add_u64 v[8:9], v[8:9], 0, v[0:1]
	v_mov_b32_e32 v0, v10
	v_lshl_add_u64 v[8:9], v[8:9], 0, v[0:1]
	global_load_dwordx4 v[120:123], v[8:9], off
	global_load_dwordx4 v[124:127], v[8:9], off offset:16
.Ltab_t5:
	s_or_b64 exec, exec, s[30:31]
	v_add_u32_e32 v19, 0xc00, v2
	v_ashrrev_i32_e32 v0, 10, v19
	v_add_u32_e32 v26, s39, v0
	v_bfe_u32 v27, v19, 6, 4
	v_lshl_or_b32 v28, v26, 4, v27
	v_ashrrev_i32_e32 v29, 31, v28
	v_lshlrev_b64 v[28:29], 10, v[28:29]
	v_lshl_add_u64 v[156:157], v[20:21], 0, v[28:29]
	v_mov_b32_e32 v128, 0
	v_mov_b32_e32 v129, 0
	v_mov_b32_e32 v130, 0
	v_mov_b32_e32 v131, 0
	v_mov_b32_e32 v132, 0
	v_mov_b32_e32 v133, 0
	v_mov_b32_e32 v134, 0
	v_mov_b32_e32 v135, 0
	v_cmp_ge_i32_e32 vcc, v26, v23
	s_and_saveexec_b64 s[30:31], vcc
	s_cbranch_execz .Ltab_t6
	v_sub_u32_e32 v0, v26, v23
	v_lshlrev_b64 v[8:9], 10, v[0:1]
	v_lshl_add_u64 v[8:9], s[26:27], 0, v[8:9]
	v_lshlrev_b32_e32 v0, 6, v27
	v_lshl_add_u64 v[8:9], v[8:9], 0, v[0:1]
	v_mov_b32_e32 v0, v10
	v_lshl_add_u64 v[8:9], v[8:9], 0, v[0:1]
	global_load_dwordx4 v[128:131], v[8:9], off
	global_load_dwordx4 v[132:135], v[8:9], off offset:16
.Ltab_t6:
	s_or_b64 exec, exec, s[30:31]
	v_add_u32_e32 v19, 0xe00, v2
	v_ashrrev_i32_e32 v0, 10, v19
	v_add_u32_e32 v26, s39, v0
	v_bfe_u32 v27, v19, 6, 4
	v_lshl_or_b32 v28, v26, 4, v27
	v_ashrrev_i32_e32 v29, 31, v28
	v_lshlrev_b64 v[28:29], 10, v[28:29]
	v_lshl_add_u64 v[158:159], v[20:21], 0, v[28:29]
	v_mov_b32_e32 v136, 0
	v_mov_b32_e32 v137, 0
	v_mov_b32_e32 v138, 0
	v_mov_b32_e32 v139, 0
	v_mov_b32_e32 v140, 0
	v_mov_b32_e32 v141, 0
	v_mov_b32_e32 v142, 0
	v_mov_b32_e32 v143, 0
	v_cmp_ge_i32_e32 vcc, v26, v23
	s_and_saveexec_b64 s[30:31], vcc
	s_cbranch_execz .Ltab_t7
	v_sub_u32_e32 v0, v26, v23
	v_lshlrev_b64 v[8:9], 10, v[0:1]
	v_lshl_add_u64 v[8:9], s[26:27], 0, v[8:9]
	v_lshlrev_b32_e32 v0, 6, v27
	v_lshl_add_u64 v[8:9], v[8:9], 0, v[0:1]
	v_mov_b32_e32 v0, v10
	v_lshl_add_u64 v[8:9], v[8:9], 0, v[0:1]
	global_load_dwordx4 v[136:139], v[8:9], off
	global_load_dwordx4 v[140:143], v[8:9], off offset:16
.Ltab_t7:
	s_or_b64 exec, exec, s[30:31]
	s_waitcnt vmcnt(0)
	v_cvt_pk_bf16_f32 v80, v80, v81
	v_cvt_pk_bf16_f32 v81, v82, v83
	v_cvt_pk_bf16_f32 v82, v84, v85
	v_cvt_pk_bf16_f32 v83, v86, v87
	global_store_dwordx4 v[144:145], v[80:83], off
	v_cvt_pk_bf16_f32 v88, v88, v89
	v_cvt_pk_bf16_f32 v89, v90, v91
	v_cvt_pk_bf16_f32 v90, v92, v93
	v_cvt_pk_bf16_f32 v91, v94, v95
	global_store_dwordx4 v[146:147], v[88:91], off
	v_cvt_pk_bf16_f32 v96, v96, v97
	v_cvt_pk_bf16_f32 v97, v98, v99
	v_cvt_pk_bf16_f32 v98, v100, v101
	v_cvt_pk_bf16_f32 v99, v102, v103
	global_store_dwordx4 v[148:149], v[96:99], off
	v_cvt_pk_bf16_f32 v104, v104, v105
	v_cvt_pk_bf16_f32 v105, v106, v107
	v_cvt_pk_bf16_f32 v106, v108, v109
	v_cvt_pk_bf16_f32 v107, v110, v111
	global_store_dwordx4 v[150:151], v[104:107], off
	v_cvt_pk_bf16_f32 v112, v112, v113
	v_cvt_pk_bf16_f32 v113, v114, v115
	v_cvt_pk_bf16_f32 v114, v116, v117
	v_cvt_pk_bf16_f32 v115, v118, v119
	global_store_dwordx4 v[152:153], v[112:115], off
	v_cvt_pk_bf16_f32 v120, v120, v121
	v_cvt_pk_bf16_f32 v121, v122, v123
	v_cvt_pk_bf16_f32 v122, v124, v125
	v_cvt_pk_bf16_f32 v123, v126, v127
	global_store_dwordx4 v[154:155], v[120:123], off
	v_cvt_pk_bf16_f32 v128, v128, v129
	v_cvt_pk_bf16_f32 v129, v130, v131
	v_cvt_pk_bf16_f32 v130, v132, v133
	v_cvt_pk_bf16_f32 v131, v134, v135
	global_store_dwordx4 v[156:157], v[128:131], off
	v_cvt_pk_bf16_f32 v136, v136, v137
	v_cvt_pk_bf16_f32 v137, v138, v139
	v_cvt_pk_bf16_f32 v138, v140, v141
	v_cvt_pk_bf16_f32 v139, v142, v143
	global_store_dwordx4 v[158:159], v[136:139], off
